# next-unit warm-up: two instead of three Q-row touches per lane (a 192-byte row always spans exactly two lines)
# baseline (speedup 1.0000x reference)
; #define LAS __attribute__((address_space(3)))
; __global__ void __launch_bounds__(512, 2) trunk_fwd(Args args) {
;     ...
;                     attn::attn_unit(bh >> 3, bh & 7, 15 - i, (const attn::bf16*)(ws + WS_Q), (const attn::bf16*)(ws + WS_KN), (const attn::bf16*)(ws + WS_KPE), (const attn::bf16*)(ws + WS_V), (attn::bf16*)(ws + WS_MIX), (float*)(ws + WS_ASS), (LAS char*)lds);
;                     attn::attn_unit(bh >> 3, bh & 7, i, (const attn::bf16*)(ws + WS_Q), (const attn::bf16*)(ws + WS_KN), (const attn::bf16*)(ws + WS_KPE), (const attn::bf16*)(ws + WS_V), (attn::bf16*)(ws + WS_MIX), (float*)(ws + WS_ASS), (LAS char*)lds);
.Lat_u1_tail:
	s_add_u32 s4, s86, 2
	s_lshl_b32 s5, s4, 16
	s_sub_u32 s5, 0, s5
	s_mov_b32 s53, -1
	s_mov_b32 vcc_lo, s5
	s_mov_b32 vcc_hi, s53
	v_lshl_add_u64 v[168:169], v[126:127], 0, vcc
	global_load_dword v155, v[168:169], off
	v_lshl_add_u64 v[168:169], v[168:169], 0, s[34:35]
	global_load_dword v155, v[168:169], off
	v_lshl_add_u64 v[168:169], v[124:125], 0, vcc
	global_load_dword v155, v[168:169], off
	v_lshl_add_u64 v[168:169], v[168:169], 0, s[34:35]
	global_load_dword v155, v[168:169], off
	s_lshl_b32 s5, s4, 12
	s_sub_u32 s5, 0, s5
	s_mov_b32 vcc_lo, s5
	v_lshl_add_u64 v[168:169], v[14:15], 0, vcc
	global_load_dword v155, v[168:169], off
	v_lshl_add_u64 v[168:169], v[168:169], 0, s[20:21]
	global_load_dword v155, v[168:169], off
	s_lshl_b32 s4, s69, 5
	s_add_u32 s4, s4, s88
	s_mul_i32 s4, s4, 0x600
	s_add_u32 s4, s4, s64
	s_add_u32 s4, s4, s78
	s_addc_u32 s5, s79, 0
	v_mul_u32_u24_e32 v172, 0x600, v140
	global_load_dword v155, v172, s[4:5]
	global_load_dword v155, v172, s[4:5] offset:128
	s_waitcnt lgkmcnt(0)
	s_lshr_b32 s4, s69, 1
	s_sub_u32 s4, s52, s4
	s_sub_u32 s4, s4, 1
	s_cmp_gt_i32 s4, s87
	s_cbranch_scc1 .Lat_u1t_skip
	s_lshl_b32 s4, s50, 13
	s_add_i32 s4, s4, 0x6000
	s_and_b32 s4, s4, 0x6000
	v_add_u32_e32 v159, s4, v144
	ds_read_b64_tr_b16 v[196:197], v159 offset:36864
	ds_read_b64_tr_b16 v[198:199], v159 offset:37376
	ds_read_b64_tr_b16 v[200:201], v159 offset:37888
	ds_read_b64_tr_b16 v[202:203], v159 offset:38400
	ds_read_b64_tr_b16 v[204:205], v159 offset:38912
	ds_read_b64_tr_b16 v[206:207], v159 offset:39424
	ds_read_b64_tr_b16 v[208:209], v159 offset:39936
	ds_read_b64_tr_b16 v[210:211], v159 offset:40448
	ds_read_b64_tr_b16 v[212:213], v159 offset:40960
	ds_read_b64_tr_b16 v[214:215], v159 offset:41472
	ds_read_b64_tr_b16 v[230:231], v159 offset:41984
	ds_read_b64_tr_b16 v[232:233], v159 offset:42496
	ds_read_b64_tr_b16 v[234:235], v159 offset:43008
	ds_read_b64_tr_b16 v[236:237], v159 offset:43520
	ds_read_b64_tr_b16 v[164:165], v159 offset:44032
	ds_read_b64_tr_b16 v[166:167], v159 offset:44544
	v_exp_f32_e32 v238, v238
	v_exp_f32_e32 v239, v239
	v_exp_f32_e32 v240, v240
	v_exp_f32_e32 v241, v241
	v_add_f32_e32 v156, v238, v239
	v_cvt_pk_bf16_f32 v238, v238, v239
	v_add_f32_e32 v157, v240, v241
	v_cvt_pk_bf16_f32 v239, v240, v241
	v_exp_f32_e32 v242, v242
	v_exp_f32_e32 v243, v243
	v_add_f32_e32 v156, v156, v242
	v_add_f32_e32 v156, v156, v243
	v_cvt_pk_bf16_f32 v240, v242, v243
	v_exp_f32_e32 v244, v244
	v_exp_f32_e32 v245, v245
	v_add_f32_e32 v157, v157, v244
	v_add_f32_e32 v157, v157, v245
	v_cvt_pk_bf16_f32 v241, v244, v245
	v_exp_f32_e32 v246, v246
	v_exp_f32_e32 v247, v247
	v_add_f32_e32 v156, v156, v246
	v_add_f32_e32 v156, v156, v247
	v_cvt_pk_bf16_f32 v242, v246, v247
	v_exp_f32_e32 v248, v248
	v_exp_f32_e32 v249, v249
	v_add_f32_e32 v157, v157, v248
	v_add_f32_e32 v157, v157, v249
	v_cvt_pk_bf16_f32 v243, v248, v249
	v_exp_f32_e32 v250, v250
	v_exp_f32_e32 v251, v251
	v_add_f32_e32 v156, v156, v250
	v_add_f32_e32 v156, v156, v251
	v_cvt_pk_bf16_f32 v244, v250, v251
	v_exp_f32_e32 v252, v252
	v_exp_f32_e32 v253, v253
	v_add_f32_e32 v157, v157, v252
	v_add_f32_e32 v157, v157, v253
	v_cvt_pk_bf16_f32 v245, v252, v253
	v_exp_f32_e32 v180, v180
	v_exp_f32_e32 v181, v181
	v_add_f32_e32 v156, v156, v180
	v_add_f32_e32 v156, v156, v181
	v_cvt_pk_bf16_f32 v180, v180, v181
	v_exp_f32_e32 v182, v182
	v_exp_f32_e32 v183, v183
	v_add_f32_e32 v157, v157, v182
	v_add_f32_e32 v157, v157, v183
	v_cvt_pk_bf16_f32 v181, v182, v183
	v_exp_f32_e32 v184, v184
	v_exp_f32_e32 v185, v185
	v_add_f32_e32 v156, v156, v184
	v_add_f32_e32 v156, v156, v185
	v_cvt_pk_bf16_f32 v182, v184, v185
	v_exp_f32_e32 v186, v186
	v_exp_f32_e32 v187, v187
	v_add_f32_e32 v157, v157, v186
	v_add_f32_e32 v157, v157, v187
	v_cvt_pk_bf16_f32 v183, v186, v187
	v_exp_f32_e32 v188, v188
	v_exp_f32_e32 v189, v189
	v_add_f32_e32 v156, v156, v188
	v_add_f32_e32 v156, v156, v189
	v_cvt_pk_bf16_f32 v184, v188, v189
	v_exp_f32_e32 v190, v190
	v_exp_f32_e32 v191, v191
	v_add_f32_e32 v157, v157, v190
	v_add_f32_e32 v157, v157, v191
	v_cvt_pk_bf16_f32 v185, v190, v191
	v_exp_f32_e32 v192, v192
	v_exp_f32_e32 v193, v193
	v_add_f32_e32 v156, v156, v192
	v_add_f32_e32 v156, v156, v193
	v_cvt_pk_bf16_f32 v186, v192, v193
	v_exp_f32_e32 v194, v194
	v_exp_f32_e32 v195, v195
	v_add_f32_e32 v157, v157, v194
	v_add_f32_e32 v157, v157, v195
	v_cvt_pk_bf16_f32 v187, v194, v195
	v_add_f32_e32 v156, v156, v157
	v_add_f32_e32 v128, v128, v156
	s_waitcnt lgkmcnt(0)
	v_mfma_f32_32x32x16_bf16 v[16:31], v[196:199], v[238:241], v[16:31]
	v_mfma_f32_32x32x16_bf16 v[32:47], v[212:215], v[238:241], v[32:47]
	v_mfma_f32_32x32x16_bf16 v[16:31], v[200:203], v[242:245], v[16:31]
	v_mfma_f32_32x32x16_bf16 v[32:47], v[230:233], v[242:245], v[32:47]
	v_mfma_f32_32x32x16_bf16 v[16:31], v[204:207], v[180:183], v[16:31]
	v_mfma_f32_32x32x16_bf16 v[32:47], v[234:237], v[180:183], v[32:47]
	v_mfma_f32_32x32x16_bf16 v[16:31], v[208:211], v[184:187], v[16:31]
	v_mfma_f32_32x32x16_bf16 v[32:47], v[164:167], v[184:187], v[32:47]

; #define LAS __attribute__((address_space(3)))
; __global__ void __launch_bounds__(512, 2) trunk_fwd(Args args) {
;     ...
;                 for (int r = 0; r < 2; ++r) {
;                     const int bh = x * 8 + r * 4 + (c >> 3);
;                     attn::attn_unit(bh >> 3, bh & 7, 15 - i, (const attn::bf16*)(ws + WS_Q), (const attn::bf16*)(ws + WS_KN), (const attn::bf16*)(ws + WS_KPE), (const attn::bf16*)(ws + WS_V), (attn::bf16*)(ws + WS_MIX), (float*)(ws + WS_ASS), (LAS char*)lds);
;                     attn::attn_unit(bh >> 3, bh & 7, i, (const attn::bf16*)(ws + WS_Q), (const attn::bf16*)(ws + WS_KN), (const attn::bf16*)(ws + WS_KPE), (const attn::bf16*)(ws + WS_V), (attn::bf16*)(ws + WS_MIX), (float*)(ws + WS_ASS), (LAS char*)lds);
.Lat_u2_tail:
	s_cmp_eq_u64 s[70:71], 0
	s_cbranch_scc1 .Lat_u2_nowarm
	s_add_u32 s4, s90, 2
	s_lshl_b32 s5, s4, 16
	s_sub_u32 s5, 0, s5
	s_mov_b32 s63, -1
	s_mov_b32 vcc_lo, s5
	s_mov_b32 vcc_hi, s63
	v_lshl_add_u64 v[168:169], v[126:127], 0, vcc
	global_load_dword v155, v[168:169], off offset:512
	v_lshl_add_u64 v[168:169], v[168:169], 0, s[34:35]
	global_load_dword v155, v[168:169], off offset:512
	v_lshl_add_u64 v[168:169], v[124:125], 0, vcc
	global_load_dword v155, v[168:169], off offset:512
	v_lshl_add_u64 v[168:169], v[168:169], 0, s[34:35]
	global_load_dword v155, v[168:169], off offset:512
	s_lshl_b32 s5, s4, 12
	s_sub_u32 s5, 0, s5
	s_mov_b32 vcc_lo, s5
	v_lshl_add_u64 v[168:169], v[122:123], 0, vcc
	global_load_dword v155, v[168:169], off
	v_lshl_add_u64 v[168:169], v[168:169], 0, s[20:21]
	global_load_dword v155, v[168:169], off
	s_lshl_b32 s4, s56, 5
	s_add_u32 s4, s4, s84
	s_mul_i32 s4, s4, 0x600
	s_add_u32 s4, s4, s64
	s_add_u32 s4, s4, 0x300
	s_add_u32 s4, s4, s78
	s_addc_u32 s5, s79, 0
	v_mul_u32_u24_e32 v172, 0x600, v141
	global_load_dword v155, v172, s[4:5]
	global_load_dword v155, v172, s[4:5] offset:128
